# adds NA scalar-base issue block and batched CL epilogue gamma loads, hot loops kept at their 8-byte placement phase
# speedup vs baseline: 1.0086x; 1.0044x over previous
.LBB0_389:
	global_load_dword v7, v[2:3], off
	s_mov_b64 s[8:9], 0x400
	v_add_u32_e32 v6, 0x100, v6
	v_lshl_add_u64 v[2:3], v[2:3], 0, s[8:9]
	s_movk_i32 s8, 0xd0
	v_cmp_lt_u32_e32 vcc, s8, v6
	s_or_b64 s[4:5], vcc, s[4:5]
	s_waitcnt vmcnt(0)
	v_mul_f32_e32 v7, 0x3fb8aa3b, v7
	ds_write_b32 v5, v7
	v_add_u32_e32 v5, 0x400, v5
	s_andn2_b64 exec, exec, s[4:5]
	s_cbranch_execnz .LBB0_389
	s_or_b64 exec, exec, s[4:5]
	s_bfe_u32 s30, s35, 0x50003
	s_and_b32 s4, s6, 32
	s_or_b32 s48, s4, s30
	v_med3_u32 v2, s48, 4, 60
	s_lshr_b32 s82, s7, 8
	v_readfirstlane_b32 s4, v2
	s_mul_i32 s6, s4, 0x58000
	s_lshl_b64 s[4:5], s[82:83], 12
	s_add_u32 s71, s4, 0x1000
	s_addc_u32 s49, s5, 0
	s_mul_i32 s4, s49, 0x2c00
	s_mul_hi_u32 s5, s71, 0x2c00
	s_add_i32 s5, s5, s4
	s_mul_i32 s4, s71, 0x2c00
	s_add_u32 s4, s38, s4
	s_addc_u32 s5, s39, s5
	s_add_u32 s8, s4, 0x1e74b200
	s_addc_u32 s9, s5, 0
	s_add_i32 s4, s6, 0xffea0000
	s_mov_b32 s5, s83
	s_lshl_b64 s[4:5], s[4:5], 1
	s_add_u32 s4, s8, s4
	s_addc_u32 s5, s9, s5
	s_bfe_u32 s31, s34, 0x10008
	s_lshl_b32 s10, s31, 5
	s_lshl_b32 s6, s82, 2
	s_or_b32 s10, s10, s30
	s_add_i32 s82, s6, s96
	v_med3_u32 v2, s10, 4, 60
	s_movk_i32 s10, 0x7c
	v_lshlrev_b32_e32 v152, 7, v0
	s_lshl_b64 s[6:7], s[82:83], 18
	v_mul_lo_u32 v5, v2, s10
	s_mul_i32 s10, s48, 0xb0000
	s_add_u32 s8, s8, s10
	v_ashrrev_i32_e32 v153, 31, v152
	s_addc_u32 s9, s9, 0
	v_lshlrev_b64 v[2:3], 1, v[152:153]
	v_lshlrev_b64 v[0:1], 15, v[0:1]
	v_lshl_add_u64 v[6:7], s[8:9], 0, v[2:3]
	v_lshl_add_u64 v[2:3], s[4:5], 0, v[2:3]
	s_mov_b64 s[4:5], 0x1000
	v_lshl_add_u64 v[0:1], v[0:1], 0, s[6:7]
	v_lshl_add_u64 v[156:157], v[2:3], 0, s[4:5]
	v_lshl_add_u64 v[0:1], v[0:1], 1, s[38:39]
	s_mov_b64 s[4:5], 0x11a04000
	v_lshl_add_u64 v[158:159], v[0:1], 0, s[4:5]
	s_mov_b64 s[4:5], 0x11e04000
	v_lshl_add_u64 v[160:161], v[0:1], 0, s[4:5]
	v_lshrrev_b32_e32 v0, 2, v167
	v_and_b32_e32 v1, 15, v167
	v_and_b32_e32 v26, 48, v0
	v_or_b32_e32 v172, v26, v1
	v_mul_u32_u24_e32 v10, 0x1600, v172
	v_and_b32_e32 v17, 3, v171
	v_lshlrev_b32_e32 v10, 1, v10
	v_mov_b32_e32 v11, v16
	v_lshl_add_u64 v[6:7], v[6:7], 0, v[10:11]
	v_lshlrev_b32_e32 v10, 4, v17
	v_or_b32_e32 v214, 48, v171
	v_lshl_add_u64 v[6:7], v[6:7], 0, v[10:11]
	v_lshlrev_b32_e32 v27, 3, v169
	global_load_dwordx4 v[50:53], v[6:7], off offset:192
	global_load_dwordx4 v[54:57], v[6:7], off offset:128
	global_load_dwordx4 v[58:61], v[6:7], off offset:64
	global_load_dwordx4 v[62:65], v[6:7], off
	v_mul_u32_u24_e32 v6, 0x1600, v214
	v_mov_b32_e32 v7, v16
	s_movk_i32 s6, 0x1600
	v_mov_b32_e32 v11, 0xfffea000
	v_and_b32_e32 v8, 0x78, v27
	v_lshlrev_b64 v[6:7], 1, v[6:7]
	v_mad_u32_u24 v18, v214, s6, v11
	v_mov_b32_e32 v19, v16
	v_lshl_add_u64 v[12:13], v[156:157], 0, v[6:7]
	v_lshlrev_b32_e32 v14, 1, v8
	v_mov_b32_e32 v15, v16
	v_lshlrev_b64 v[18:19], 1, v[18:19]
	v_lshl_add_u64 v[12:13], v[12:13], 0, v[14:15]
	v_lshl_add_u64 v[20:21], v[156:157], 0, v[18:19]
	v_mov_b32_e32 v11, 0xfffd4000
	v_lshl_add_u64 v[20:21], v[20:21], 0, v[14:15]
	global_load_dwordx4 v[66:69], v[12:13], off
	global_load_dwordx4 v[70:73], v[20:21], off
	v_mad_u32_u24 v12, v214, s6, v11
	v_mov_b32_e32 v13, v16
	v_lshlrev_b64 v[12:13], 1, v[12:13]
	v_mul_u32_u24_e32 v22, 0x1600, v171
	v_mov_b32_e32 v23, v16
	v_lshl_add_u64 v[20:21], v[156:157], 0, v[12:13]
	v_lshlrev_b64 v[22:23], 1, v[22:23]
	v_lshl_add_u64 v[6:7], v[2:3], 0, v[6:7]
	v_lshl_add_u64 v[20:21], v[20:21], 0, v[14:15]
	v_lshl_add_u64 v[24:25], v[156:157], 0, v[22:23]
	v_lshl_add_u64 v[6:7], v[6:7], 0, v[14:15]
	v_lshl_add_u64 v[18:19], v[2:3], 0, v[18:19]
	v_lshl_add_u64 v[24:25], v[24:25], 0, v[14:15]
	global_load_dwordx4 v[74:77], v[20:21], off
	global_load_dwordx4 v[78:81], v[24:25], off
	v_lshl_add_u64 v[18:19], v[18:19], 0, v[14:15]
	global_load_dwordx4 v[86:89], v[6:7], off offset:2048
	global_load_dwordx4 v[94:97], v[18:19], off offset:2048
	v_lshl_add_u64 v[6:7], v[2:3], 0, v[12:13]
	v_lshl_add_u64 v[154:155], v[2:3], 0, s[94:95]
	v_lshl_add_u64 v[6:7], v[6:7], 0, v[14:15]
	v_lshl_add_u64 v[2:3], v[2:3], 0, v[22:23]
	v_lshlrev_b32_e32 v12, 4, v1
	v_mov_b32_e32 v13, v16
	v_lshl_add_u64 v[2:3], v[2:3], 0, v[12:13]
	global_load_dwordx4 v[82:85], v[6:7], off offset:2048
	global_load_dwordx4 v[90:93], v[2:3], off offset:2048
	v_and_b32_e32 v23, 64, v191
	v_xor_b32_e32 v22, 16, v191
	v_add_u32_e32 v23, 64, v23
	v_cmp_lt_i32_e32 vcc, v22, v23
	v_add_u32_e32 v9, 0, v4
	v_or_b32_e32 v182, 16, v171
	v_cndmask_b32_e32 v22, v191, v22, vcc
	v_or_b32_e32 v183, 32, v171
	v_lshlrev_b32_e32 v173, 2, v17
	v_and_b32_e32 v15, 24, v27
	v_lshlrev_b32_e32 v178, 2, v22
	v_xor_b32_e32 v22, 32, v191
	v_bitop3_b32 v24, v17, v1, 4 bitop3:0x36
	v_bitop3_b32 v17, v17, v1, 8 bitop3:0x36
	v_lshl_add_u32 v2, v171, 8, v9
	v_lshl_add_u32 v6, v182, 8, v9
	v_lshl_add_u32 v11, v183, 8, v9
	v_lshl_add_u32 v12, v214, 8, v9
	v_mad_u32_u24 v215, v171, s92, v9
	v_bfe_u32 v14, v167, 2, 2
	v_cmp_lt_i32_e32 vcc, v22, v23
	v_lshl_add_u32 v23, v1, 8, v9
	v_lshlrev_b32_e32 v25, 4, v17
	v_bitop3_b32 v17, v171, v1, 12 bitop3:0x36
	v_add_u32_e32 v9, v9, v15
	v_or_b32_e32 v15, 32, v173
	v_or_b32_e32 v28, 7, v26
	v_med3_u32 v20, v172, 8, 56
	v_lshlrev_b32_e32 v27, 4, v17
	v_or_b32_e32 v17, v173, v14
	v_or_b32_e32 v14, v15, v14
	v_add_u32_e32 v21, -8, v20
	v_cmp_lt_u32_e64 s[10:11], 16, v28
	v_cmp_lt_u32_e64 s[12:13], 32, v28
	v_mul_u32_u24_e32 v28, 0x120, v14
	v_or_b32_e32 v14, 1, v173
	v_cmp_ge_u32_e64 s[16:17], v14, v21
	v_or_b32_e32 v14, 2, v173
	v_cmp_ge_u32_e64 s[18:19], v14, v21
	v_or_b32_e32 v14, 3, v173
	v_add_u32_e32 v20, 8, v20
	v_cmp_ge_u32_e64 s[20:21], v14, v21
	v_or_b32_e32 v14, 16, v173
	v_cndmask_b32_e32 v22, v191, v22, vcc
	v_cmp_ge_u32_e32 vcc, v14, v21
	v_cmp_lt_u32_e64 s[22:23], v14, v20
	v_or_b32_e32 v14, 17, v173
	s_and_b64 s[52:53], vcc, s[22:23]
	v_cmp_ge_u32_e32 vcc, v14, v21
	v_cmp_lt_u32_e64 s[22:23], v14, v20
	v_or_b32_e32 v14, 18, v173
	s_and_b64 s[94:95], vcc, s[22:23]
	v_cmp_ge_u32_e32 vcc, v14, v21
	v_cmp_lt_u32_e64 s[22:23], v14, v20
	v_or_b32_e32 v14, 19, v173
	s_and_b64 s[76:77], vcc, s[22:23]
	v_cmp_ge_u32_e32 vcc, v14, v21
	v_cmp_lt_u32_e64 s[22:23], v14, v20
	s_and_b64 s[60:61], vcc, s[22:23]
	v_cmp_ge_u32_e32 vcc, v15, v21
	v_cmp_lt_u32_e64 s[22:23], v15, v20
	v_or_b32_e32 v14, 33, v173
	s_and_b64 s[62:63], vcc, s[22:23]
	v_cmp_ge_u32_e32 vcc, v14, v21
	v_cmp_lt_u32_e64 s[22:23], v14, v20
	v_or_b32_e32 v14, 34, v173
	s_and_b64 s[68:69], vcc, s[22:23]
	v_cmp_ge_u32_e32 vcc, v14, v21
	v_cmp_lt_u32_e64 s[22:23], v14, v20
	v_or_b32_e32 v14, 35, v173
	v_lshlrev_b32_e32 v0, 3, v1
	v_lshlrev_b32_e32 v179, 2, v22
	v_bitop3_b32 v22, v171, v1, 3 bitop3:0x6c
	s_and_b64 s[92:93], vcc, s[22:23]
	v_cmp_ge_u32_e32 vcc, v14, v21
	v_cmp_lt_u32_e64 s[22:23], v14, v20
	v_or_b32_e32 v14, 48, v173
	v_add3_u32 v4, v4, v5, v10
	v_lshlrev_b32_e32 v1, 2, v1
	s_and_b64 s[96:97], vcc, s[22:23]
	v_cmp_lt_u32_e64 s[22:23], v14, v20
	v_or_b32_e32 v14, 49, v173
	v_sub_u32_e32 v1, v4, v1
	v_and_b32_e32 v4, 0xc0, v167
	s_mulk_i32 s30, 0x7c
	v_xor_b32_e32 v7, v171, v169
	v_lshlrev_b32_e32 v13, 4, v169
	v_cmp_lt_u32_e64 s[24:25], v14, v20
	v_or_b32_e32 v14, 50, v173
	v_sub_u32_e32 v1, v1, v4
	s_mulk_i32 s31, 0xf80
	v_bitop3_b32 v3, v171, v167, 15 bitop3:0x78
	v_lshlrev_b32_e32 v7, 4, v7
	v_and_b32_e32 v216, 0xf0, v13
	v_add_u32_e32 v18, 0x2400, v215
	v_add_u32_e32 v19, 0x3600, v215
	v_lshlrev_b32_e32 v22, 4, v22
	v_lshlrev_b32_e32 v24, 4, v24
	v_cmp_gt_u32_e64 s[6:7], 17, v26
	v_cmp_gt_u32_e64 s[8:9], 33, v26
	v_mul_u32_u24_e32 v26, 0x120, v17
	v_cmp_lt_u32_e64 s[26:27], v14, v20
	v_or_b32_e32 v14, 51, v173
	v_subrev_u32_e32 v1, s30, v1
	v_mov_b32_e32 v17, v16
	v_lshlrev_b32_e32 v3, 4, v3
	v_and_b32_e32 v7, 0xf0, v7
	v_add_u32_e32 v13, 0x1200, v215
	v_cmp_ge_u32_e64 s[14:15], v173, v21
	v_cmp_lt_u32_e64 s[28:29], v14, v20
	v_subrev_u32_e32 v1, s31, v1
	v_readlane_b32 s30, v255, 12
	v_mov_b32_e32 v14, v16
	v_mov_b32_e32 v15, v16
	v_add_u32_e32 v223, v18, v216
	v_add_u32_e32 v224, v19, v216
	v_add_u32_e32 v220, v23, v22
	v_add_u32_e32 v219, v23, v24
	v_add_u32_e32 v218, v23, v25
	v_add_u32_e32 v217, v23, v27
	v_add_u32_e32 v181, v9, v26
	v_add_u32_e32 v180, v9, v28
	v_mov_b64_e32 v[48:49], v[16:17]
	v_mov_b64_e32 v[44:45], v[16:17]
	v_mov_b64_e32 v[40:41], v[16:17]
	v_mov_b64_e32 v[36:37], v[16:17]
	v_mov_b64_e32 v[32:33], v[16:17]
	v_mov_b64_e32 v[28:29], v[16:17]
	v_mov_b64_e32 v[24:25], v[16:17]
	v_mov_b64_e32 v[20:21], v[16:17]
	v_cmp_gt_u32_e64 s[4:5], 64, v169
	s_mov_b32 s82, 0
	v_add_u32_e32 v221, s30, v1
	v_mov_b32_e32 v230, 0xf149f2ca
	v_mov_b32_e32 v229, 0
	v_lshlrev_b32_e32 v162, 1, v0
	v_lshlrev_b32_e32 v164, 1, v8
	v_add_u32_e32 v225, v2, v3
	v_add_u32_e32 v226, v6, v7
	v_add_u32_e32 v227, v11, v7
	v_add_u32_e32 v228, v12, v7
	v_add_u32_e32 v222, v13, v216
	v_mov_b64_e32 v[46:47], v[14:15]
	v_mov_b64_e32 v[42:43], v[14:15]
	v_mov_b64_e32 v[38:39], v[14:15]
	v_mov_b64_e32 v[34:35], v[14:15]
	v_mov_b64_e32 v[30:31], v[14:15]
	v_mov_b64_e32 v[26:27], v[14:15]
	v_mov_b64_e32 v[22:23], v[14:15]
	v_mov_b64_e32 v[18:19], v[14:15]
	s_nop 0
	s_movk_i32 s66, 0x2c00
	v_mad_u32_u24 v236, v171, s66, v162
	v_mad_u32_u24 v237, v171, s66, v164
	v_mad_u32_u24 v238, v182, s66, v164
	v_mad_u32_u24 v239, v183, s66, v164
	v_mad_u32_u24 v240, v214, s66, v164
	v_lshl_add_u32 v241, v171, 8, v162
	v_lshl_add_u32 v242, v171, 8, v164
	v_lshl_add_u32 v243, v182, 8, v164
	v_lshl_add_u32 v244, v183, 8, v164
	v_lshl_add_u32 v245, v214, 8, v164

.LBB0_466:
	v_readlane_b32 s68, v255, 16
	v_readlane_b32 s70, v255, 18
	s_mov_b64 s[4:5], 0
	v_readlane_b32 s69, v255, 17
	s_nop 0
	v_readlane_b32 s71, v255, 19
